# grid barrier: groups are hardware XCC ids (registered through the first barrier); only the last arriver of an XCD writes its L2 back, instead of every workgroup
# speedup vs baseline: 1.0333x; 1.0191x over previous
; __device__ __forceinline__ int ltid() { return launder((int)threadIdx.x); }
; __device__ __forceinline__ void prologue(const Params& P) {
;   unsigned char* ws = P.ws; const int tid = ltid();
;   if (blockIdx.x == 0 && tid < 64) {
;     unsigned* ctl = (unsigned*)(ws + WS_CTL);
;     if (tid < 8 || (tid >= 16 && tid < 48)) ctl[tid] = 0u;
; __global__ void __launch_bounds__(512) mega(Params P) {
;   cg::grid_group grid = cg::this_grid();
;   unsigned char* ws = P.ws;
;   if (EN & 1) prologue(P);
_Z4mega6Params:
	s_mov_b32 s96, 1
	v_writelane_b32 v255, s96, 24
	s_load_dwordx16 s[4:19], s[0:1], 0x40
	s_add_u32 s56, s0, 0xa0
	s_load_dword s52, s[0:1], 0xa0
	s_addc_u32 s57, s1, 0
	v_and_b32_e32 v155, 0x3ff, v0
	s_waitcnt lgkmcnt(0)
	v_writelane_b32 v253, s4, 0
	v_mov_b32_e32 v4, v155
	s_cmp_eq_u32 s2, 0
	v_writelane_b32 v253, s5, 1
	v_writelane_b32 v253, s6, 2
	v_writelane_b32 v253, s7, 3
	v_writelane_b32 v253, s8, 4
	v_writelane_b32 v253, s9, 5
	v_writelane_b32 v253, s10, 6
	v_writelane_b32 v253, s11, 7
	v_writelane_b32 v253, s12, 8
	v_writelane_b32 v253, s13, 9
	v_writelane_b32 v253, s14, 10
	v_writelane_b32 v253, s15, 11
	v_writelane_b32 v253, s16, 12
	v_writelane_b32 v253, s17, 13
	v_writelane_b32 v253, s18, 14
	v_writelane_b32 v253, s19, 15
	s_load_dwordx8 s[4:11], s[0:1], 0x80
	s_mov_b32 s37, s2
	s_cselect_b64 s[2:3], -1, 0
	v_cmp_gt_i32_e32 vcc, 64, v4
	s_waitcnt lgkmcnt(0)
	v_writelane_b32 v253, s4, 16
	s_and_b64 s[2:3], s[2:3], vcc
	s_nop 0
	v_writelane_b32 v253, s5, 17
	v_writelane_b32 v253, s6, 18
	v_writelane_b32 v253, s7, 19
	v_writelane_b32 v253, s8, 20
	v_writelane_b32 v253, s9, 21
	v_writelane_b32 v253, s10, 22
	v_writelane_b32 v253, s11, 23
	s_and_saveexec_b64 s[4:5], s[2:3]
	s_cbranch_execz .LBB0_15
	v_add_u32_e32 v1, -16, v4
	v_cmp_lt_i32_e32 vcc, 7, v4
	v_cmp_lt_u32_e64 s[2:3], 31, v1
	s_and_b64 s[2:3], vcc, s[2:3]
	v_mov_b32_e32 v5, 0
	s_and_saveexec_b64 s[6:7], s[2:3]
	s_xor_b64 s[2:3], exec, s[6:7]
	s_or_saveexec_b64 s[2:3], s[2:3]
	v_mov_b64_e32 v[6:7], v[4:5]
	s_xor_b64 exec, exec, s[2:3]
	s_cbranch_execz .LBB0_3
	s_load_dwordx8 s[8:15], s[0:1], 0x80
	v_ashrrev_i32_e32 v7, 31, v4
	v_mov_b32_e32 v6, v4
	v_mov_b32_e32 v1, 0
	s_waitcnt lgkmcnt(0)
	v_lshl_add_u64 v[2:3], v[6:7], 2, s[14:15]
	global_store_dword v[2:3], v1, off

; __global__ void __launch_bounds__(512) mega(Params P) {
;     ...
;   grid.sync();
.Ln1_done:
.LBB0_225:
	s_or_b64 exec, exec, s[4:5]
	s_barrier
	s_mov_b64 s[2:3], exec
	v_readlane_b32 s0, v253, 57
	v_readlane_b32 s1, v253, 58
	s_and_b64 s[0:1], s[2:3], s[0:1]
	s_mov_b64 exec, s[0:1]
	s_cbranch_execz .LBB0_235
	s_load_dwordx2 s[4:5], s[56:57], -0x8
	v_readlane_b32 s96, v255, 24
	s_waitcnt lgkmcnt(0)
	s_cmp_eq_u32 s96, 0
	s_cbranch_scc1 .Lgbx_new_0
	buffer_wbl2 sc1
	s_load_dword s0, s[56:57], 0x0
	v_readlane_b32 s1, v253, 55
	s_getreg_b32 s97, hwreg(HW_REG_XCC_ID, 0, 4)
	v_writelane_b32 v255, s97, 21
	s_lshr_b32 s98, s97, 2
	s_lshl_b32 s98, s98, 2
	s_addk_i32 s98, 0xa8
	s_and_b32 s99, s97, 3
	s_lshl_b32 s99, s99, 3
	s_lshl_b32 s99, 1, s99
	v_mov_b32_e32 v2, s98
	v_mov_b32_e32 v3, s99
	global_atomic_add v3, v2, v3, s[4:5] sc0
	s_waitcnt vmcnt(0) lgkmcnt(0)
	s_and_b32 s1, s1, 7
	s_add_i32 s6, s0, 7
	s_sub_i32 s6, s6, s1
	s_lshr_b32 s6, s6, 3
	s_min_u32 s7, s0, 8
	s_branch .Lgbx_arr_0
.Lgbx_new_0:
	v_readlane_b32 s1, v255, 21
	v_readlane_b32 s6, v255, 22
	v_readlane_b32 s7, v255, 23
	s_nop 3
.Lgbx_arr_0:
	s_lshl_b32 s1, s1, 2
	s_addk_i32 s1, 0x88
	v_mov_b32_e32 v2, s1
	global_load_dword v0, v1, s[4:5] sc1
	v_mov_b32_e32 v3, 1
	s_waitcnt vmcnt(0)
	v_and_b32_e32 v0, 0xffff0000, v0
	global_atomic_add v3, v2, v3, s[4:5] sc0
	s_waitcnt vmcnt(0)
	v_and_b32_e32 v3, 0xffff, v3
	s_nop 0
	v_readfirstlane_b32 s1, v3
	s_nop 3
	s_add_i32 s0, s6, -1
	s_cmp_lg_u32 s1, s0
	s_cbranch_scc1 .Lgbx_poll_0
	s_cmp_eq_u32 s96, 0
	s_cbranch_scc0 .Lgbx_nofl_0
	buffer_wbl2 sc1
	s_waitcnt vmcnt(0)
.Lgbx_nofl_0:
	s_sub_i32 s1, 0x10000, s6
	v_mov_b32_e32 v3, s1
	global_atomic_add v3, v2, v3, s[4:5] sc0
	s_waitcnt vmcnt(0)
	v_mov_b32_e32 v3, 1
	global_atomic_add v3, v1, v3, s[4:5] sc0
	s_waitcnt vmcnt(0)
	v_and_b32_e32 v3, 0xffff, v3
	s_nop 0
	v_readfirstlane_b32 s1, v3
	s_nop 3
	s_add_i32 s0, s7, -1
	s_cmp_lg_u32 s1, s0
	s_cbranch_scc1 .Lgbx_poll_0
	s_sub_i32 s1, 0x10000, s7
	v_mov_b32_e32 v3, s1
	global_atomic_add v1, v3, s[4:5]

; __global__ void __launch_bounds__(512) mega(Params P) {
;     ...
;   grid.sync();
.Lgbx_sw_0:
	s_cmp_eq_u32 s96, 0
	s_cbranch_scc1 .Lgb_done_0
	global_load_dwordx2 v[2:3], v1, s[4:5] offset:168 sc1
	s_waitcnt vmcnt(0)
	v_readfirstlane_b32 s0, v2
	v_readfirstlane_b32 s1, v3
	v_readlane_b32 s97, v255, 21
	s_nop 3
	s_lshl_b32 s98, s97, 3
	s_lshr_b64 s[98:99], s[0:1], s98
	s_and_b32 s98, s98, 0xff
	v_writelane_b32 v255, s98, 22
	s_and_b32 s99, s0, 0x7f7f7f7f
	s_add_u32 s99, s99, 0x7f7f7f7f
	s_or_b32 s99, s99, s0
	s_and_b32 s99, s99, 0x80808080
	s_bcnt1_i32_b32 s0, s99
	s_and_b32 s99, s1, 0x7f7f7f7f
	s_add_u32 s99, s99, 0x7f7f7f7f
	s_or_b32 s99, s99, s1
	s_and_b32 s99, s99, 0x80808080
	s_bcnt1_i32_b32 s1, s99
	s_add_i32 s0, s0, s1
	v_writelane_b32 v255, s0, 23
	s_mov_b32 s0, 0
	v_writelane_b32 v255, s0, 24

; __global__ void __launch_bounds__(512) mega(Params P) {
;     ...
;     grid.sync();
.LBB0_769:
	s_waitcnt vmcnt(0) lgkmcnt(0)
	s_barrier
	s_mov_b64 s[2:3], exec
	v_readlane_b32 s0, v253, 57
	v_readlane_b32 s1, v253, 58
	s_and_b64 s[0:1], s[2:3], s[0:1]
	s_mov_b64 exec, s[0:1]
	s_cbranch_execz .LBB0_779
	s_load_dwordx2 s[4:5], s[56:57], -0x8
	v_readlane_b32 s96, v255, 24
	s_waitcnt lgkmcnt(0)
	s_cmp_eq_u32 s96, 0
	s_cbranch_scc1 .Lgbx_new_1
	buffer_wbl2 sc1
	s_load_dword s0, s[56:57], 0x0
	v_readlane_b32 s1, v253, 55
	s_getreg_b32 s97, hwreg(HW_REG_XCC_ID, 0, 4)
	v_writelane_b32 v255, s97, 21
	s_lshr_b32 s98, s97, 2
	s_lshl_b32 s98, s98, 2
	s_addk_i32 s98, 0xa8
	s_and_b32 s99, s97, 3
	s_lshl_b32 s99, s99, 3
	s_lshl_b32 s99, 1, s99
	v_mov_b32_e32 v2, s98
	v_mov_b32_e32 v3, s99
	global_atomic_add v3, v2, v3, s[4:5] sc0
	s_waitcnt vmcnt(0) lgkmcnt(0)
	s_and_b32 s1, s1, 7
	s_add_i32 s6, s0, 7
	s_sub_i32 s6, s6, s1
	s_lshr_b32 s6, s6, 3
	s_min_u32 s7, s0, 8
	s_branch .Lgbx_arr_1

; __global__ void __launch_bounds__(512) mega(Params P) {
;     ...
;     grid.sync();
.LBB0_1207:
	s_barrier
	s_mov_b64 s[2:3], exec
	v_readlane_b32 s0, v253, 57
	v_readlane_b32 s1, v253, 58
	s_and_b64 s[0:1], s[2:3], s[0:1]
	s_mov_b64 exec, s[0:1]
	s_cbranch_execz .LBB0_1217
	s_load_dwordx2 s[4:5], s[56:57], -0x8
	v_readlane_b32 s96, v255, 24
	s_waitcnt lgkmcnt(0)
	s_cmp_eq_u32 s96, 0
	s_cbranch_scc1 .Lgbx_new_2
	buffer_wbl2 sc1
	s_load_dword s0, s[56:57], 0x0
	v_readlane_b32 s1, v253, 55
	s_getreg_b32 s97, hwreg(HW_REG_XCC_ID, 0, 4)
	v_writelane_b32 v255, s97, 21
	s_lshr_b32 s98, s97, 2
	s_lshl_b32 s98, s98, 2
	s_addk_i32 s98, 0xa8
	s_and_b32 s99, s97, 3
	s_lshl_b32 s99, s99, 3
	s_lshl_b32 s99, 1, s99
	v_mov_b32_e32 v2, s98
	v_mov_b32_e32 v3, s99
	global_atomic_add v3, v2, v3, s[4:5] sc0
	s_waitcnt vmcnt(0) lgkmcnt(0)
	s_and_b32 s1, s1, 7
	s_add_i32 s6, s0, 7
	s_sub_i32 s6, s6, s1
	s_lshr_b32 s6, s6, 3
	s_min_u32 s7, s0, 8
	s_branch .Lgbx_arr_2

; __global__ void __launch_bounds__(512) mega(Params P) {
;     ...
;     grid.sync();
.LBB0_1432:
	s_waitcnt lgkmcnt(0)
	s_barrier
	s_mov_b64 s[2:3], exec
	v_readlane_b32 s0, v253, 57
	v_readlane_b32 s1, v253, 58
	v_readlane_b32 s56, v254, 50
	s_and_b64 s[0:1], s[2:3], s[0:1]
	v_readlane_b32 s52, v254, 52
	v_readlane_b32 s57, v254, 51
	v_readlane_b32 s53, v254, 53
	s_mov_b64 exec, s[0:1]
	s_cbranch_execz .LBB0_1442
	s_load_dwordx2 s[4:5], s[56:57], -0x8
	v_readlane_b32 s96, v255, 24
	s_waitcnt lgkmcnt(0)
	s_cmp_eq_u32 s96, 0
	s_cbranch_scc1 .Lgbx_new_3
	buffer_wbl2 sc1
	s_load_dword s0, s[56:57], 0x0
	v_readlane_b32 s1, v253, 55
	s_getreg_b32 s97, hwreg(HW_REG_XCC_ID, 0, 4)
	v_writelane_b32 v255, s97, 21
	s_lshr_b32 s98, s97, 2
	s_lshl_b32 s98, s98, 2
	s_addk_i32 s98, 0xa8
	s_and_b32 s99, s97, 3
	s_lshl_b32 s99, s99, 3
	s_lshl_b32 s99, 1, s99
	v_mov_b32_e32 v2, s98
	v_mov_b32_e32 v3, s99
	global_atomic_add v3, v2, v3, s[4:5] sc0
	s_waitcnt vmcnt(0) lgkmcnt(0)
	s_and_b32 s1, s1, 7
	s_add_i32 s6, s0, 7
	s_sub_i32 s6, s6, s1
	s_lshr_b32 s6, s6, 3
	s_min_u32 s7, s0, 8
	s_branch .Lgbx_arr_3

; __global__ void __launch_bounds__(512) mega(Params P) {
;     ...
;     grid.sync();
.LBB0_1489:
	s_waitcnt lgkmcnt(0)
	s_barrier
	s_mov_b64 s[4:5], exec
	v_readlane_b32 s0, v253, 57
	v_readlane_b32 s1, v253, 58
	s_and_b64 s[0:1], s[4:5], s[0:1]
	s_mov_b64 exec, s[0:1]
	s_cbranch_execz .LBB0_1499
	s_load_dwordx2 s[6:7], s[56:57], -0x8
	v_readlane_b32 s96, v255, 24
	s_waitcnt lgkmcnt(0)
	s_cmp_eq_u32 s96, 0
	s_cbranch_scc1 .Lgbx_new_4
	buffer_wbl2 sc1
	s_load_dword s0, s[56:57], 0x0
	v_readlane_b32 s1, v253, 55
	s_getreg_b32 s97, hwreg(HW_REG_XCC_ID, 0, 4)
	v_writelane_b32 v255, s97, 21
	s_lshr_b32 s98, s97, 2
	s_lshl_b32 s98, s98, 2
	s_addk_i32 s98, 0xa8
	s_and_b32 s99, s97, 3
	s_lshl_b32 s99, s99, 3
	s_lshl_b32 s99, 1, s99
	v_mov_b32_e32 v2, s98
	v_mov_b32_e32 v3, s99
	global_atomic_add v3, v2, v3, s[6:7] sc0
	s_waitcnt vmcnt(0) lgkmcnt(0)
	s_and_b32 s1, s1, 7
	s_add_i32 s8, s0, 7
	s_sub_i32 s8, s8, s1
	s_lshr_b32 s8, s8, 3
	s_min_u32 s9, s0, 8
	s_branch .Lgbx_arr_4
.Lgbx_new_4:
	v_readlane_b32 s1, v255, 21
	v_readlane_b32 s8, v255, 22
	v_readlane_b32 s9, v255, 23
	s_nop 3
.Lgbx_arr_4:
	s_lshl_b32 s1, s1, 2
	s_addk_i32 s1, 0x88
	v_mov_b32_e32 v2, s1
	global_load_dword v0, v1, s[6:7] sc1
	v_mov_b32_e32 v3, 1
	s_waitcnt vmcnt(0)
	v_and_b32_e32 v0, 0xffff0000, v0
	global_atomic_add v3, v2, v3, s[6:7] sc0
	s_waitcnt vmcnt(0)
	v_and_b32_e32 v3, 0xffff, v3
	s_nop 0
	v_readfirstlane_b32 s1, v3
	s_nop 3
	s_add_i32 s0, s8, -1
	s_cmp_lg_u32 s1, s0
	s_cbranch_scc1 .Lgbx_poll_4
	s_cmp_eq_u32 s96, 0
	s_cbranch_scc0 .Lgbx_nofl_4
	buffer_wbl2 sc1
	s_waitcnt vmcnt(0)
.Lgbx_nofl_4:
	s_sub_i32 s1, 0x10000, s8
	v_mov_b32_e32 v3, s1
	global_atomic_add v3, v2, v3, s[6:7] sc0
	s_waitcnt vmcnt(0)
	v_mov_b32_e32 v3, 1
	global_atomic_add v3, v1, v3, s[6:7] sc0
	s_waitcnt vmcnt(0)
	v_and_b32_e32 v3, 0xffff, v3
	s_nop 0
	v_readfirstlane_b32 s1, v3
	s_nop 3
	s_add_i32 s0, s9, -1
	s_cmp_lg_u32 s1, s0
	s_cbranch_scc1 .Lgbx_poll_4
	s_sub_i32 s1, 0x10000, s9
	v_mov_b32_e32 v3, s1
	global_atomic_add v1, v3, s[6:7]

; __global__ void __launch_bounds__(512) mega(Params P) {
;     ...
;     grid.sync();
.Lgbx_sw_4:
	s_cmp_eq_u32 s96, 0
	s_cbranch_scc1 .Lgb_done_4
	global_load_dwordx2 v[2:3], v1, s[6:7] offset:168 sc1
	s_waitcnt vmcnt(0)
	v_readfirstlane_b32 s0, v2
	v_readfirstlane_b32 s1, v3
	v_readlane_b32 s97, v255, 21
	s_nop 3
	s_lshl_b32 s98, s97, 3
	s_lshr_b64 s[98:99], s[0:1], s98
	s_and_b32 s98, s98, 0xff
	v_writelane_b32 v255, s98, 22
	s_and_b32 s99, s0, 0x7f7f7f7f
	s_add_u32 s99, s99, 0x7f7f7f7f
	s_or_b32 s99, s99, s0
	s_and_b32 s99, s99, 0x80808080
	s_bcnt1_i32_b32 s0, s99
	s_and_b32 s99, s1, 0x7f7f7f7f
	s_add_u32 s99, s99, 0x7f7f7f7f
	s_or_b32 s99, s99, s1
	s_and_b32 s99, s99, 0x80808080
	s_bcnt1_i32_b32 s1, s99
	s_add_i32 s0, s0, s1
	v_writelane_b32 v255, s0, 23
	s_mov_b32 s0, 0
	v_writelane_b32 v255, s0, 24

; __global__ void __launch_bounds__(512) mega(Params P) {
;     ...
;     grid.sync();
.Ln2_done:
.LBB0_1502:
	s_or_b64 exec, exec, s[6:7]
	s_barrier
	s_mov_b64 s[4:5], exec
	v_readlane_b32 s0, v253, 57
	v_readlane_b32 s1, v253, 58
	s_and_b64 s[0:1], s[4:5], s[0:1]
	s_mov_b64 exec, s[0:1]
	s_cbranch_execz .LBB0_1512
	s_load_dwordx2 s[6:7], s[56:57], -0x8
	v_readlane_b32 s96, v255, 24
	s_waitcnt lgkmcnt(0)
	s_cmp_eq_u32 s96, 0
	s_cbranch_scc1 .Lgbx_new_5
	buffer_wbl2 sc1
	s_load_dword s0, s[56:57], 0x0
	v_readlane_b32 s1, v253, 55
	s_getreg_b32 s97, hwreg(HW_REG_XCC_ID, 0, 4)
	v_writelane_b32 v255, s97, 21
	s_lshr_b32 s98, s97, 2
	s_lshl_b32 s98, s98, 2
	s_addk_i32 s98, 0xa8
	s_and_b32 s99, s97, 3
	s_lshl_b32 s99, s99, 3
	s_lshl_b32 s99, 1, s99
	v_mov_b32_e32 v2, s98
	v_mov_b32_e32 v3, s99
	global_atomic_add v3, v2, v3, s[6:7] sc0
	s_waitcnt vmcnt(0) lgkmcnt(0)
	s_and_b32 s1, s1, 7
	s_add_i32 s8, s0, 7
	s_sub_i32 s8, s8, s1
	s_lshr_b32 s8, s8, 3
	s_min_u32 s9, s0, 8
	s_branch .Lgbx_arr_5

; __global__ void __launch_bounds__(512) mega(Params P) {
;     ...
;     grid.sync();
.LBB0_1534:
	s_waitcnt vmcnt(0) lgkmcnt(0)
	s_barrier
	s_mov_b64 s[4:5], exec
	v_readlane_b32 s0, v253, 57
	v_readlane_b32 s1, v253, 58
	s_and_b64 s[0:1], s[4:5], s[0:1]
	s_mov_b64 exec, s[0:1]
	s_cbranch_execz .LBB0_1544
	s_load_dwordx2 s[6:7], s[56:57], -0x8
	v_readlane_b32 s96, v255, 24
	s_waitcnt lgkmcnt(0)
	s_cmp_eq_u32 s96, 0
	s_cbranch_scc1 .Lgbx_new_6
	buffer_wbl2 sc1
	s_load_dword s0, s[56:57], 0x0
	v_readlane_b32 s1, v253, 55
	s_getreg_b32 s97, hwreg(HW_REG_XCC_ID, 0, 4)
	v_writelane_b32 v255, s97, 21
	s_lshr_b32 s98, s97, 2
	s_lshl_b32 s98, s98, 2
	s_addk_i32 s98, 0xa8
	s_and_b32 s99, s97, 3
	s_lshl_b32 s99, s99, 3
	s_lshl_b32 s99, 1, s99
	v_mov_b32_e32 v2, s98
	v_mov_b32_e32 v3, s99
	global_atomic_add v3, v2, v3, s[6:7] sc0
	s_waitcnt vmcnt(0) lgkmcnt(0)
	s_and_b32 s1, s1, 7
	s_add_i32 s8, s0, 7
	s_sub_i32 s8, s8, s1
	s_lshr_b32 s8, s8, 3
	s_min_u32 s9, s0, 8
	s_branch .Lgbx_arr_6

; __global__ void __launch_bounds__(512) mega(Params P) {
;     ...
;     grid.sync();
.LBB0_1567:
	s_load_dwordx2 s[4:5], s[56:57], -0x8
	v_readlane_b32 s96, v255, 24
	s_waitcnt lgkmcnt(0)
	s_cmp_eq_u32 s96, 0
	s_cbranch_scc1 .Lgbx_new_7
	buffer_wbl2 sc1
	s_load_dword s0, s[56:57], 0x0
	v_readlane_b32 s1, v253, 55
	s_getreg_b32 s97, hwreg(HW_REG_XCC_ID, 0, 4)
	v_writelane_b32 v255, s97, 21
	s_lshr_b32 s98, s97, 2
	s_lshl_b32 s98, s98, 2
	s_addk_i32 s98, 0xa8
	s_and_b32 s99, s97, 3
	s_lshl_b32 s99, s99, 3
	s_lshl_b32 s99, 1, s99
	v_mov_b32_e32 v2, s98
	v_mov_b32_e32 v3, s99
	global_atomic_add v3, v2, v3, s[4:5] sc0
	s_waitcnt vmcnt(0) lgkmcnt(0)
	s_and_b32 s1, s1, 7
	s_add_i32 s6, s0, 7
	s_sub_i32 s6, s6, s1
	s_lshr_b32 s6, s6, 3
	s_min_u32 s7, s0, 8
	s_branch .Lgbx_arr_7
